# sample attention loop: forget-bias inputs not waited at loop top (same fix as prompt loop)
# speedup vs baseline: 1.0287x; 1.0048x over previous
; __device__ __forceinline__ void attn_sample_unit(const Args& a, LAS unsigned char* lds, const int h, const int b, const int tid_in, const int lane_in, const int wave) {
;     ...
;         if (tid < 128) { const int j = 2 * i + (tid >> 6); ckst = j < 32 ? (pfc[j] + cltc[j * 64 + (tid & 63)]) * L2E : (pfs + CLT[MP + b * 64 + (tid & 63)]) * L2E; }
.LBB0_469:
	v_cmp_gt_i32_e32 vcc, 32, v183
	v_mov_b32_e32 v36, s13
	v_mov_b64_e32 v[34:35], s[4:5]
	v_mov_b32_e32 v197, v173
	s_and_saveexec_b64 s[10:11], vcc
	s_cbranch_execz .LBB0_471
	global_load_dword v197, v[128:129], off
	v_add_u32_e32 v36, s14, v182
	v_mov_b64_e32 v[34:35], s[6:7]
.LBB0_471:
	s_or_b64 exec, exec, s[10:11]
	v_or_b32_e32 v36, v36, v119
	v_ashrrev_i32_e32 v37, 31, v36
	v_lshl_add_u64 v[34:35], v[36:37], 2, v[34:35]
	global_load_dword v198, v[34:35], off
	s_or_b64 exec, exec, s[0:1]
	s_andn2_b64 vcc, exec, s[42:43]
	s_cbranch_vccnz .LBB0_482

; #define LAS __attribute__((address_space(3)))
; __device__ __forceinline__ void attn_sample_unit(const Args& a, LAS unsigned char* lds, const int h, const int b, const int tid_in, const int lane_in, const int wave) {
;     ...
;             *(LAS u32x4*)(lds + AS_K + t * AT_KB + sr * 144 + sc8 * 16) = kw; *(LAS u32x4*)(lds + AS_V + t * AT_VB + sr * 160 + sc8 * 16) = vw; }
;         if (tid < 128) *(LAS float*)(lds + AS_CK + tid * 4) = ckst;
.LBB0_486:
	ds_write_b128 v175, v[34:37] offset:9216
	ds_write_b128 v176, v[38:41] offset:28672
	s_and_saveexec_b64 s[0:1], s[2:3]
	s_cbranch_execz .LBB0_462
	s_waitcnt vmcnt(0)
	v_add_f32_e32 v95, v197, v198
	v_mul_f32_e32 v95, 0x3fb8aa3b, v95
	ds_write_b32 v177, v95 offset:38912
	s_branch .LBB0_462
